# same as previous best with larger spin caps in the barrier / rendezvous wait loops (robustness)
# baseline (speedup 1.0000x reference)
.LBB0_105:
	s_waitcnt vmcnt(0) lgkmcnt(0)
	v_mov_b32_e32 v128, v192
	s_barrier
	s_load_dwordx2 s[2:3], s[0:1], 0xf0
	v_readfirstlane_b32 s6, v128
	s_waitcnt lgkmcnt(0)
	s_add_u32 s4, s2, 0x27a0000
	v_writelane_b32 v248, s2, 2
	s_addc_u32 s5, s3, 0
	s_nop 0
	v_writelane_b32 v248, s3, 3
	v_writelane_b32 v248, s4, 4
	s_getreg_b32 s2, hwreg(HW_REG_XCC_ID, 0, 4)
	s_and_b32 s2, s2, 15
	v_writelane_b32 v248, s5, 5
	v_writelane_b32 v248, s2, 6
	v_cmp_eq_u32_e64 s[4:5], 0, v192
	s_mov_b64 s[2:3], exec
	s_nop 0
	v_writelane_b32 v248, s4, 7
	s_nop 1
	v_writelane_b32 v248, s5, 8
	s_and_b64 s[4:5], s[2:3], s[4:5]
	s_mov_b64 exec, s[4:5]
	s_cbranch_execz .LBB0_118
	v_writelane_b32 v249, s10, 10
	v_writelane_b32 v249, s11, 11
	v_writelane_b32 v249, s12, 12
	v_writelane_b32 v249, s13, 13
	v_readlane_b32 s4, v248, 4
	v_readlane_b32 s5, v248, 5
	v_readlane_b32 s7, v248, 6
	v_mov_b32_e32 v250, 0
	v_mov_b32_e32 v252, 1
	v_mov_b32_e32 v0, 0x3400
	s_mov_b32 s12, 0x7f4a7c15
	s_mov_b32 s13, 0x9e3779b9
	s_add_u32 s10, s4, 0x10000
	s_addc_u32 s11, s5, 0
	s_mov_b32 s9, 0x400000

.Lgb0_magic_ok:
	s_lshl_b32 s8, s7, 8
	v_mov_b32_e32 v251, s8
	s_nop 0
	global_atomic_add v251, v252, s[4:5] offset:1024
	s_mov_b64 exec, 0xffff
	v_lshlrev_b32_e32 v253, 8, v192
	s_mov_b32 s9, 0x400000

.Lgb0_fwait:
	s_mov_b32 s11, 0x400000

.Lhb1_fwait:
	s_mov_b32 s12, 0x400000

.LBB0_1340:
	v_or_b32_e32 v0, s20, v55
	v_mad_i64_i32 v[48:49], s[20:21], v0, s14, v[34:35]
	v_or_b32_e32 v0, s19, v55
	v_mul_u32_u24_e32 v4, 0xb00, v0
	global_load_dwordx4 v[0:3], v[48:49], off
	v_lshlrev_b32_e32 v4, 1, v4
	v_mov_b32_e32 v5, v33
	v_lshl_add_u64 v[104:105], v[36:37], 0, v[4:5]
	global_load_dwordx4 v[4:7], v[104:105], off
	v_add_co_u32_e32 v106, vcc, s15, v104
	v_ashrrev_i32_e32 v45, 31, v44
	s_nop 0
	v_addc_co_u32_e32 v107, vcc, 0, v105, vcc
	global_load_dwordx4 v[8:11], v[106:107], off
	global_load_dwordx4 v[72:75], v[48:49], off offset:32
	global_load_dwordx4 v[76:79], v[104:105], off offset:32
	global_load_dwordx4 v[80:83], v[48:49], off offset:672
	global_load_dwordx4 v[84:87], v[106:107], off offset:32
	global_load_dwordx4 v[88:91], v[48:49], off offset:64
	global_load_dwordx4 v[92:95], v[104:105], off offset:672
	global_load_dwordx4 v[96:99], v[104:105], off offset:64
	s_add_i32 s18, s18, s92
	s_add_i32 s8, s8, s9
	s_add_i32 s10, s10, s11
	s_cmpk_lt_i32 s18, 0x100
	s_waitcnt vmcnt(8)
	v_mfma_f32_32x32x16_bf16 v[16:31], v[0:3], v[4:7], 0
	s_waitcnt vmcnt(7)
	v_mfma_f32_32x32x16_bf16 v[0:15], v[0:3], v[8:11], 0
	s_waitcnt vmcnt(5)
	v_mfma_f32_32x32x16_bf16 v[16:31], v[72:75], v[76:79], v[16:31]
	global_load_dwordx4 v[76:79], v[106:107], off offset:64
	global_load_dwordx4 v[100:103], v[48:49], off offset:96
	s_waitcnt vmcnt(5)
	v_mfma_f32_32x32x16_bf16 v[0:15], v[72:75], v[84:87], v[0:15]
	global_load_dwordx4 v[72:75], v[104:105], off offset:96
	s_waitcnt vmcnt(3)
	v_mfma_f32_32x32x16_bf16 v[16:31], v[88:91], v[96:99], v[16:31]
	global_load_dwordx4 v[84:87], v[106:107], off offset:96
	global_load_dwordx4 v[96:99], v[48:49], off offset:128
	s_waitcnt vmcnt(4)
	v_mfma_f32_32x32x16_bf16 v[0:15], v[88:91], v[76:79], v[0:15]
	global_load_dwordx4 v[76:79], v[104:105], off offset:128
	s_waitcnt vmcnt(3)
	v_mfma_f32_32x32x16_bf16 v[16:31], v[100:103], v[72:75], v[16:31]
	global_load_dwordx4 v[72:75], v[106:107], off offset:128
	global_load_dwordx4 v[88:91], v[48:49], off offset:160
	s_waitcnt vmcnt(4)
	v_mfma_f32_32x32x16_bf16 v[0:15], v[100:103], v[84:87], v[0:15]
	global_load_dwordx4 v[84:87], v[104:105], off offset:160
	s_waitcnt vmcnt(3)
	v_mfma_f32_32x32x16_bf16 v[16:31], v[96:99], v[76:79], v[16:31]
	global_load_dwordx4 v[76:79], v[106:107], off offset:160
	global_load_dwordx4 v[100:103], v[48:49], off offset:192
	s_waitcnt vmcnt(4)
	v_mfma_f32_32x32x16_bf16 v[0:15], v[96:99], v[72:75], v[0:15]
	global_load_dwordx4 v[72:75], v[104:105], off offset:192
	s_waitcnt vmcnt(3)
	v_mfma_f32_32x32x16_bf16 v[16:31], v[88:91], v[84:87], v[16:31]
	global_load_dwordx4 v[84:87], v[106:107], off offset:192
	global_load_dwordx4 v[96:99], v[48:49], off offset:224
	s_waitcnt vmcnt(4)
	v_mfma_f32_32x32x16_bf16 v[0:15], v[88:91], v[76:79], v[0:15]
	global_load_dwordx4 v[76:79], v[104:105], off offset:224
	s_waitcnt vmcnt(3)
	v_mfma_f32_32x32x16_bf16 v[16:31], v[100:103], v[72:75], v[16:31]
	global_load_dwordx4 v[72:75], v[106:107], off offset:224
	global_load_dwordx4 v[88:91], v[48:49], off offset:256
	s_waitcnt vmcnt(4)
	v_mfma_f32_32x32x16_bf16 v[0:15], v[100:103], v[84:87], v[0:15]
	global_load_dwordx4 v[84:87], v[104:105], off offset:256
	s_waitcnt vmcnt(3)
	v_mfma_f32_32x32x16_bf16 v[16:31], v[96:99], v[76:79], v[16:31]
	global_load_dwordx4 v[76:79], v[106:107], off offset:256
	global_load_dwordx4 v[100:103], v[48:49], off offset:288
	s_waitcnt vmcnt(4)
	v_mfma_f32_32x32x16_bf16 v[0:15], v[96:99], v[72:75], v[0:15]
	global_load_dwordx4 v[72:75], v[104:105], off offset:288
	s_waitcnt vmcnt(3)
	v_mfma_f32_32x32x16_bf16 v[16:31], v[88:91], v[84:87], v[16:31]
	global_load_dwordx4 v[84:87], v[106:107], off offset:288
	global_load_dwordx4 v[96:99], v[48:49], off offset:320
	s_waitcnt vmcnt(4)
	v_mfma_f32_32x32x16_bf16 v[0:15], v[88:91], v[76:79], v[0:15]
	global_load_dwordx4 v[76:79], v[104:105], off offset:320
	s_waitcnt vmcnt(3)
	v_mfma_f32_32x32x16_bf16 v[16:31], v[100:103], v[72:75], v[16:31]
	global_load_dwordx4 v[72:75], v[106:107], off offset:320
	global_load_dwordx4 v[88:91], v[48:49], off offset:352
	s_waitcnt vmcnt(4)
	v_mfma_f32_32x32x16_bf16 v[0:15], v[100:103], v[84:87], v[0:15]
	global_load_dwordx4 v[84:87], v[104:105], off offset:352
	s_waitcnt vmcnt(3)
	v_mfma_f32_32x32x16_bf16 v[16:31], v[96:99], v[76:79], v[16:31]
	global_load_dwordx4 v[76:79], v[106:107], off offset:352
	global_load_dwordx4 v[100:103], v[48:49], off offset:384
	s_waitcnt vmcnt(4)
	v_mfma_f32_32x32x16_bf16 v[0:15], v[96:99], v[72:75], v[0:15]
	global_load_dwordx4 v[72:75], v[104:105], off offset:384
	s_waitcnt vmcnt(3)
	v_mfma_f32_32x32x16_bf16 v[16:31], v[88:91], v[84:87], v[16:31]
	global_load_dwordx4 v[84:87], v[106:107], off offset:384
	global_load_dwordx4 v[96:99], v[48:49], off offset:416
	s_waitcnt vmcnt(4)
	v_mfma_f32_32x32x16_bf16 v[0:15], v[88:91], v[76:79], v[0:15]
	global_load_dwordx4 v[76:79], v[104:105], off offset:416
	s_waitcnt vmcnt(3)
	v_mfma_f32_32x32x16_bf16 v[16:31], v[100:103], v[72:75], v[16:31]
	global_load_dwordx4 v[72:75], v[106:107], off offset:416
	global_load_dwordx4 v[88:91], v[48:49], off offset:448
	s_waitcnt vmcnt(4)
	v_mfma_f32_32x32x16_bf16 v[0:15], v[100:103], v[84:87], v[0:15]
	global_load_dwordx4 v[84:87], v[104:105], off offset:448
	s_waitcnt vmcnt(3)
	v_mfma_f32_32x32x16_bf16 v[16:31], v[96:99], v[76:79], v[16:31]
	global_load_dwordx4 v[76:79], v[106:107], off offset:448
	global_load_dwordx4 v[100:103], v[48:49], off offset:480
	s_waitcnt vmcnt(4)
	v_mfma_f32_32x32x16_bf16 v[0:15], v[96:99], v[72:75], v[0:15]
	global_load_dwordx4 v[72:75], v[104:105], off offset:480
	s_waitcnt vmcnt(3)
	v_mfma_f32_32x32x16_bf16 v[16:31], v[88:91], v[84:87], v[16:31]
	global_load_dwordx4 v[84:87], v[106:107], off offset:480
	global_load_dwordx4 v[96:99], v[48:49], off offset:512
	s_waitcnt vmcnt(4)
	v_mfma_f32_32x32x16_bf16 v[0:15], v[88:91], v[76:79], v[0:15]
	global_load_dwordx4 v[76:79], v[104:105], off offset:512
	s_waitcnt vmcnt(3)
	v_mfma_f32_32x32x16_bf16 v[16:31], v[100:103], v[72:75], v[16:31]
	global_load_dwordx4 v[72:75], v[106:107], off offset:512
	global_load_dwordx4 v[88:91], v[48:49], off offset:544
	s_waitcnt vmcnt(4)
	v_mfma_f32_32x32x16_bf16 v[0:15], v[100:103], v[84:87], v[0:15]
	global_load_dwordx4 v[84:87], v[104:105], off offset:544
	s_waitcnt vmcnt(3)
	v_mfma_f32_32x32x16_bf16 v[16:31], v[96:99], v[76:79], v[16:31]
	global_load_dwordx4 v[76:79], v[106:107], off offset:544
	global_load_dwordx4 v[100:103], v[48:49], off offset:576
	s_waitcnt vmcnt(4)
	v_mfma_f32_32x32x16_bf16 v[0:15], v[96:99], v[72:75], v[0:15]
	global_load_dwordx4 v[72:75], v[104:105], off offset:576
	s_waitcnt vmcnt(3)
	v_mfma_f32_32x32x16_bf16 v[16:31], v[88:91], v[84:87], v[16:31]
	global_load_dwordx4 v[84:87], v[106:107], off offset:576
	s_waitcnt vmcnt(3)
	v_mfma_f32_32x32x16_bf16 v[0:15], v[88:91], v[76:79], v[0:15]
	s_waitcnt vmcnt(1)
	v_mfma_f32_32x32x16_bf16 v[16:31], v[100:103], v[72:75], v[16:31]
	global_load_dwordx4 v[72:75], v[48:49], off offset:608
	s_waitcnt vmcnt(1)
	v_mfma_f32_32x32x16_bf16 v[0:15], v[100:103], v[84:87], v[0:15]
	global_load_dwordx4 v[76:79], v[104:105], off offset:608
	global_load_dwordx4 v[84:87], v[48:49], off offset:640
	global_load_dwordx4 v[88:91], v[104:105], off offset:640
	v_lshlrev_b64 v[48:49], 11, v[44:45]
	v_lshl_add_u64 v[46:47], v[46:47], 0, v[48:49]
	s_waitcnt vmcnt(2)
	v_mfma_f32_32x32x16_bf16 v[16:31], v[72:75], v[76:79], v[16:31]
	global_load_dwordx4 v[76:79], v[106:107], off offset:608
	global_load_dwordx4 v[96:99], v[106:107], off offset:640
	s_nop 0
	global_load_ushort v46, v[46:47], off
	v_lshlrev_b32_e32 v47, 16, v71
	s_waitcnt vmcnt(2)
	v_mfma_f32_32x32x16_bf16 v[0:15], v[72:75], v[76:79], v[0:15]
	global_load_dwordx4 v[72:75], v[106:107], off offset:672
	v_mfma_f32_32x32x16_bf16 v[16:31], v[84:87], v[88:91], v[16:31]
	s_waitcnt vmcnt(2)
	v_mfma_f32_32x32x16_bf16 v[0:15], v[84:87], v[96:99], v[0:15]
	v_mfma_f32_32x32x16_bf16 v[16:31], v[80:83], v[92:95], v[16:31]
	s_waitcnt vmcnt(0)
	v_mfma_f32_32x32x16_bf16 v[0:15], v[80:83], v[72:75], v[0:15]
	s_nop 9
	ds_write2st64_b32 v56, v16, v17 offset1:1
	ds_write2st64_b32 v56, v18, v19 offset0:2 offset1:3
	ds_write2st64_b32 v56, v20, v21 offset0:4 offset1:5
	ds_write2st64_b32 v56, v22, v23 offset0:6 offset1:7
	ds_write2st64_b32 v56, v24, v25 offset0:8 offset1:9
	ds_write2st64_b32 v56, v26, v27 offset0:10 offset1:11
	ds_write2st64_b32 v56, v28, v29 offset0:12 offset1:13
	ds_write2st64_b32 v56, v30, v31 offset0:14 offset1:15
	ds_write2st64_b32 v56, v0, v1 offset0:16 offset1:17
	ds_write2st64_b32 v56, v2, v3 offset0:18 offset1:19
	ds_write2st64_b32 v56, v4, v5 offset0:20 offset1:21
	ds_write2st64_b32 v56, v6, v7 offset0:22 offset1:23
	ds_write2st64_b32 v56, v8, v9 offset0:24 offset1:25
	ds_write2st64_b32 v56, v10, v11 offset0:26 offset1:27
	ds_write2st64_b32 v56, v12, v13 offset0:28 offset1:29
	ds_write2st64_b32 v56, v14, v15 offset0:30 offset1:31
	s_waitcnt lgkmcnt(0)
	s_barrier
	ds_read2st64_b32 v[0:1], v57 offset1:32
	ds_read2st64_b32 v[2:3], v57 offset0:64 offset1:96
	ds_read2st64_b32 v[4:5], v57 offset0:128 offset1:160
	v_lshlrev_b32_e32 v7, 16, v69
	v_lshlrev_b32_e32 v6, 16, v70
	s_waitcnt lgkmcnt(2)
	v_add_f32_e32 v0, 0, v0
	v_add_f32_e32 v0, v0, v1
	s_waitcnt lgkmcnt(1)
	v_add_f32_e32 v2, v0, v2
	ds_read2st64_b32 v[0:1], v57 offset0:192 offset1:224
	v_add_f32_e32 v2, v2, v3
	s_waitcnt lgkmcnt(1)
	v_add_f32_e32 v4, v2, v4
	ds_read2st64_b32 v[2:3], v58 offset1:32
	v_add_f32_e32 v4, v4, v5
	s_waitcnt lgkmcnt(1)
	v_add_f32_e32 v0, v4, v0
	ds_read2st64_b32 v[4:5], v58 offset0:64 offset1:96
	v_add_f32_e32 v9, v0, v1
	s_waitcnt lgkmcnt(1)
	v_add_f32_e32 v2, 0, v2
	ds_read2st64_b32 v[0:1], v58 offset0:128 offset1:160
	v_add_f32_e32 v2, v2, v3
	s_waitcnt lgkmcnt(1)
	v_add_f32_e32 v4, v2, v4
	ds_read2st64_b32 v[2:3], v58 offset0:192 offset1:224
	v_add_f32_e32 v4, v4, v5
	s_waitcnt lgkmcnt(1)
	v_add_f32_e32 v0, v4, v0
	ds_read2st64_b32 v[4:5], v59 offset1:32
	v_add_f32_e32 v0, v0, v1
	s_waitcnt lgkmcnt(1)
	v_add_f32_e32 v2, v0, v2
	ds_read2st64_b32 v[0:1], v59 offset0:64 offset1:96
	v_add_f32_e32 v10, v2, v3
	s_waitcnt lgkmcnt(1)
	v_add_f32_e32 v4, 0, v4
	ds_read2st64_b32 v[2:3], v59 offset0:128 offset1:160
	v_add_f32_e32 v4, v4, v5
	s_waitcnt lgkmcnt(1)
	v_add_f32_e32 v0, v4, v0
	ds_read2st64_b32 v[4:5], v59 offset0:192 offset1:224
	v_add_f32_e32 v0, v0, v1
	s_waitcnt lgkmcnt(1)
	v_add_f32_e32 v2, v0, v2
	ds_read2st64_b32 v[0:1], v60 offset1:32
	v_add_f32_e32 v2, v2, v3
	s_waitcnt lgkmcnt(1)
	v_add_f32_e32 v2, v2, v4
	v_add_f32_e32 v11, v2, v5
	ds_read2st64_b32 v[2:3], v60 offset0:64 offset1:96
	ds_read2st64_b32 v[4:5], v60 offset0:128 offset1:160
	s_waitcnt lgkmcnt(2)
	v_add_f32_e32 v0, 0, v0
	v_add_f32_e32 v12, v0, v1
	ds_read2st64_b32 v[0:1], v60 offset0:192 offset1:224
	s_waitcnt lgkmcnt(2)
	v_add_f32_e32 v2, v12, v2
	v_add_f32_e32 v2, v2, v3
	s_waitcnt lgkmcnt(1)
	v_add_f32_e32 v2, v2, v4
	v_add_f32_e32 v2, v2, v5
	s_waitcnt lgkmcnt(0)
	v_add_f32_e32 v0, v2, v0
	v_add_f32_e32 v2, v0, v1
	s_load_dwordx2 s[40:41], s[0:1], 0xf0
	s_load_dwordx4 s[44:47], s[0:1], 0xd8
	v_add_f32_e32 v12, v62, v9
	v_mul_f32_e32 v12, v61, v12
	v_fmac_f32_e32 v12, 0x3f9837f0, v7
	s_barrier
	v_lshlrev_b32_e32 v8, 16, v46
	v_add_f32_e32 v13, v65, v10
	v_mul_f32_e32 v13, v64, v13
	v_fmac_f32_e32 v13, 0x3f9837f0, v6
	v_add_f32_e32 v14, v63, v11
	v_mul_f32_e32 v14, v66, v14
	v_fmac_f32_e32 v14, 0x3f9837f0, v47
	v_add_f32_e32 v15, v68, v2
	v_mul_f32_e32 v15, v67, v15
	v_fmac_f32_e32 v15, 0x3f9837f0, v8
	s_lshr_b32 s48, s96, 4
	s_and_b32 s49, s96, 15
	s_lshl_b32 s51, s49, 3
	s_waitcnt lgkmcnt(0)
	global_load_dword v16, v32, s[44:45]
	global_load_dword v17, v32, s[46:47]
	s_lshl_b32 s50, s48, 12
	s_add_u32 s42, s40, 0xff00000
	s_addc_u32 s43, s41, 0
	s_add_u32 s42, s42, s50
	s_addc_u32 s43, s43, 0
	s_lshl_b32 s50, s48, 8
	s_add_u32 s40, s40, 0x27a4080
	s_addc_u32 s41, s41, 0
	s_add_u32 s40, s40, s50
	s_addc_u32 s41, s41, 0
	v_mov_b32_e32 v24, v12
	v_mov_b32_e32 v26, v13
	v_mov_b32_e32 v28, v14
	v_mov_b32_e32 v30, v15
	s_nop 1
	v_add_f32_dpp v24, v24, v24 quad_perm:[1,0,3,2] row_mask:0xf bank_mask:0xf
	v_add_f32_dpp v26, v26, v26 quad_perm:[1,0,3,2] row_mask:0xf bank_mask:0xf
	v_add_f32_dpp v28, v28, v28 quad_perm:[1,0,3,2] row_mask:0xf bank_mask:0xf
	v_add_f32_dpp v30, v30, v30 quad_perm:[1,0,3,2] row_mask:0xf bank_mask:0xf
	v_add_f32_dpp v24, v24, v24 quad_perm:[2,3,0,1] row_mask:0xf bank_mask:0xf
	v_add_f32_dpp v26, v26, v26 quad_perm:[2,3,0,1] row_mask:0xf bank_mask:0xf
	v_add_f32_dpp v28, v28, v28 quad_perm:[2,3,0,1] row_mask:0xf bank_mask:0xf
	v_add_f32_dpp v30, v30, v30 quad_perm:[2,3,0,1] row_mask:0xf bank_mask:0xf
	v_add_f32_dpp v24, v24, v24 row_half_mirror row_mask:0xf bank_mask:0xf
	v_add_f32_dpp v26, v26, v26 row_half_mirror row_mask:0xf bank_mask:0xf
	v_add_f32_dpp v28, v28, v28 row_half_mirror row_mask:0xf bank_mask:0xf
	v_add_f32_dpp v30, v30, v30 row_half_mirror row_mask:0xf bank_mask:0xf
	v_add_f32_dpp v24, v24, v24 row_mirror row_mask:0xf bank_mask:0xf
	v_add_f32_dpp v26, v26, v26 row_mirror row_mask:0xf bank_mask:0xf
	v_add_f32_dpp v28, v28, v28 row_mirror row_mask:0xf bank_mask:0xf
	v_add_f32_dpp v30, v30, v30 row_mirror row_mask:0xf bank_mask:0xf
	s_nop 1
	v_readlane_b32 s52, v24, 0
	v_readlane_b32 s53, v24, 16
	v_readlane_b32 s54, v24, 32
	v_readlane_b32 s55, v24, 48
	v_readlane_b32 s56, v26, 0
	v_readlane_b32 s57, v26, 16
	v_readlane_b32 s58, v26, 32
	v_readlane_b32 s59, v26, 48
	v_readlane_b32 s60, v28, 0
	v_readlane_b32 s61, v28, 16
	v_readlane_b32 s62, v28, 32
	v_readlane_b32 s63, v28, 48
	v_readlane_b32 s64, v30, 0
	v_readlane_b32 s65, v30, 16
	v_readlane_b32 s66, v30, 32
	v_readlane_b32 s67, v30, 48
	v_mov_b32_e32 v24, s52
	v_add_f32_e32 v24, s53, v24
	v_add_f32_e32 v24, s54, v24
	v_add_f32_e32 v24, s55, v24
	v_mov_b32_e32 v26, s56
	v_add_f32_e32 v26, s57, v26
	v_add_f32_e32 v26, s58, v26
	v_add_f32_e32 v26, s59, v26
	v_mov_b32_e32 v28, s60
	v_add_f32_e32 v28, s61, v28
	v_add_f32_e32 v28, s62, v28
	v_add_f32_e32 v28, s63, v28
	v_mov_b32_e32 v30, s64
	v_add_f32_e32 v30, s65, v30
	v_add_f32_e32 v30, s66, v30
	v_add_f32_e32 v30, s67, v30
	v_mul_f32_e32 v24, 0x3c800000, v24
	v_mul_f32_e32 v26, 0x3c800000, v26
	v_mul_f32_e32 v28, 0x3c800000, v28
	v_mul_f32_e32 v30, 0x3c800000, v30
	v_sub_f32_e32 v25, v12, v24
	v_sub_f32_e32 v27, v13, v26
	v_sub_f32_e32 v29, v14, v28
	v_sub_f32_e32 v31, v15, v30
	v_mul_f32_e32 v25, v25, v25
	v_mul_f32_e32 v27, v27, v27
	v_mul_f32_e32 v29, v29, v29
	v_mul_f32_e32 v31, v31, v31
	s_nop 1
	v_add_f32_dpp v25, v25, v25 quad_perm:[1,0,3,2] row_mask:0xf bank_mask:0xf
	v_add_f32_dpp v27, v27, v27 quad_perm:[1,0,3,2] row_mask:0xf bank_mask:0xf
	v_add_f32_dpp v29, v29, v29 quad_perm:[1,0,3,2] row_mask:0xf bank_mask:0xf
	v_add_f32_dpp v31, v31, v31 quad_perm:[1,0,3,2] row_mask:0xf bank_mask:0xf
	v_add_f32_dpp v25, v25, v25 quad_perm:[2,3,0,1] row_mask:0xf bank_mask:0xf
	v_add_f32_dpp v27, v27, v27 quad_perm:[2,3,0,1] row_mask:0xf bank_mask:0xf
	v_add_f32_dpp v29, v29, v29 quad_perm:[2,3,0,1] row_mask:0xf bank_mask:0xf
	v_add_f32_dpp v31, v31, v31 quad_perm:[2,3,0,1] row_mask:0xf bank_mask:0xf
	v_add_f32_dpp v25, v25, v25 row_half_mirror row_mask:0xf bank_mask:0xf
	v_add_f32_dpp v27, v27, v27 row_half_mirror row_mask:0xf bank_mask:0xf
	v_add_f32_dpp v29, v29, v29 row_half_mirror row_mask:0xf bank_mask:0xf
	v_add_f32_dpp v31, v31, v31 row_half_mirror row_mask:0xf bank_mask:0xf
	v_add_f32_dpp v25, v25, v25 row_mirror row_mask:0xf bank_mask:0xf
	v_add_f32_dpp v27, v27, v27 row_mirror row_mask:0xf bank_mask:0xf
	v_add_f32_dpp v29, v29, v29 row_mirror row_mask:0xf bank_mask:0xf
	v_add_f32_dpp v31, v31, v31 row_mirror row_mask:0xf bank_mask:0xf
	s_nop 1
	v_readlane_b32 s52, v25, 0
	v_readlane_b32 s53, v25, 16
	v_readlane_b32 s54, v25, 32
	v_readlane_b32 s55, v25, 48
	v_readlane_b32 s56, v27, 0
	v_readlane_b32 s57, v27, 16
	v_readlane_b32 s58, v27, 32
	v_readlane_b32 s59, v27, 48
	v_readlane_b32 s60, v29, 0
	v_readlane_b32 s61, v29, 16
	v_readlane_b32 s62, v29, 32
	v_readlane_b32 s63, v29, 48
	v_readlane_b32 s64, v31, 0
	v_readlane_b32 s65, v31, 16
	v_readlane_b32 s66, v31, 32
	v_readlane_b32 s67, v31, 48
	v_mov_b32_e32 v25, s52
	v_add_f32_e32 v25, s53, v25
	v_add_f32_e32 v25, s54, v25
	v_add_f32_e32 v25, s55, v25
	v_mov_b32_e32 v27, s56
	v_add_f32_e32 v27, s57, v27
	v_add_f32_e32 v27, s58, v27
	v_add_f32_e32 v27, s59, v27
	v_mov_b32_e32 v29, s60
	v_add_f32_e32 v29, s61, v29
	v_add_f32_e32 v29, s62, v29
	v_add_f32_e32 v29, s63, v29
	v_mov_b32_e32 v31, s64
	v_add_f32_e32 v31, s65, v31
	v_add_f32_e32 v31, s66, v31
	v_add_f32_e32 v31, s67, v31
	v_lshlrev_b32_e32 v20, 7, v51
	v_add_u32_e32 v20, s51, v20
	v_mov_b32_e32 v21, 0
	v_mov_b32_e32 v22, 1
	s_mov_b64 exec, 1
	global_store_dwordx2 v20, v[24:25], s[42:43] sc1
	global_store_dwordx2 v20, v[26:27], s[42:43] offset:1024 sc1
	global_store_dwordx2 v20, v[28:29], s[42:43] offset:2048 sc1
	global_store_dwordx2 v20, v[30:31], s[42:43] offset:3072 sc1
	s_waitcnt vmcnt(0)
	global_atomic_add v21, v22, s[40:41]
	s_mov_b64 exec, -1
	v_lshrrev_b32_e32 v20, 4, v50
	v_lshlrev_b32_e32 v20, 10, v20
	v_and_b32_e32 v23, 15, v50
	v_lshl_add_u32 v20, v23, 3, v20
	v_lshl_add_u32 v20, v51, 7, v20
	v_readfirstlane_b32 s58, v51
	s_mov_b32 s56, 0x400000
	s_cmp_lg_u32 s58, 0
	s_cbranch_scc1 .Lp12_go
